# weight conversion: gain loads of a tile go to own registers, one wait + 8 multiplies after the 4th tile load (4 dependent round trips -> 1), 8 conv_load instances
# speedup vs baseline: 1.0095x; 1.0095x over previous
.LBB0_268:
	s_waitcnt vmcnt(10)
	v_ashrrev_i32_e32 v24, 5, v22
	v_add_u32_e32 v8, s10, v24
	v_mad_i64_i32 v[6:7], s[4:5], s14, v8, 0
	v_and_b32_e32 v2, 60, v23
	v_lshl_add_u64 v[6:7], v[6:7], 2, s[16:17]
	v_ashrrev_i32_e32 v5, 31, v4
	v_lshl_add_u64 v[4:5], v[4:5], 2, v[6:7]
	v_lshlrev_b32_e32 v2, 2, v2
	v_lshl_add_u64 v[4:5], v[4:5], 0, v[2:3]
	global_load_dwordx4 v[4:7], v[4:5], off
	s_cmp_lg_u64 s[12:13], 0
	s_cselect_b64 s[18:19], -1, 0
	s_cmp_eq_u64 s[12:13], 0
	s_cbranch_scc1 .LBB0_270
	v_ashrrev_i32_e32 v9, 31, v8
	v_lshl_add_u64 v[8:9], v[8:9], 2, s[12:13]
	global_load_dword v242, v[8:9], off

.LBB0_272:
	v_add_u32_e32 v9, 0x200, v22
	v_ashrrev_i32_e32 v25, 5, v9
	v_add_u32_e32 v12, s10, v25
	v_mad_i64_i32 v[10:11], s[4:5], s14, v12, 0
	v_lshl_add_u64 v[10:11], v[10:11], 2, s[16:17]
	v_ashrrev_i32_e32 v9, 31, v8
	v_lshl_add_u64 v[8:9], v[8:9], 2, v[10:11]
	v_lshl_add_u64 v[8:9], v[8:9], 0, v[2:3]
	global_load_dwordx4 v[8:11], v[8:9], off
	v_cndmask_b32_e64 v13, 0, 1, s[18:19]
	v_cmp_ne_u32_e64 s[4:5], 1, v13
	s_andn2_b64 vcc, exec, s[18:19]
	s_cbranch_vccnz .LBB0_274
	v_ashrrev_i32_e32 v13, 31, v12
	v_lshl_add_u64 v[12:13], v[12:13], 2, s[12:13]
	global_load_dword v244, v[12:13], off

.LBB0_276:
	v_add_u32_e32 v13, 0x400, v22
	v_ashrrev_i32_e32 v26, 5, v13
	v_add_u32_e32 v18, s10, v26
	v_mad_i64_i32 v[14:15], s[18:19], s14, v18, 0
	v_lshl_add_u64 v[14:15], v[14:15], 2, s[16:17]
	v_ashrrev_i32_e32 v13, 31, v12
	v_lshl_add_u64 v[12:13], v[12:13], 2, v[14:15]
	v_lshl_add_u64 v[12:13], v[12:13], 0, v[2:3]
	global_load_dwordx4 v[12:15], v[12:13], off
	s_and_b64 vcc, exec, s[4:5]
	s_cbranch_vccnz .LBB0_278
	v_ashrrev_i32_e32 v19, 31, v18
	v_lshl_add_u64 v[18:19], v[18:19], 2, s[12:13]
	global_load_dword v246, v[18:19], off

.LBB0_280:
	v_add_u32_e32 v17, 0x600, v22
	v_ashrrev_i32_e32 v27, 5, v17
	v_add_u32_e32 v20, s10, v27
	v_mad_i64_i32 v[18:19], s[0:1], s14, v20, 0
	v_lshl_add_u64 v[18:19], v[18:19], 2, s[16:17]
	v_ashrrev_i32_e32 v17, 31, v16
	v_lshl_add_u64 v[16:17], v[16:17], 2, v[18:19]
	v_lshl_add_u64 v[16:17], v[16:17], 0, v[2:3]
	global_load_dwordx4 v[16:19], v[16:17], off
	s_and_b64 vcc, exec, s[4:5]
	s_cbranch_vccnz .LBB0_282
	v_ashrrev_i32_e32 v21, 31, v20
	v_lshl_add_u64 v[20:21], v[20:21], 2, s[12:13]
	global_load_dword v248, v[20:21], off
	s_waitcnt vmcnt(0)
	v_pk_mul_f32 v[6:7], v[6:7], v[242:243] op_sel_hi:[1,0]
	v_pk_mul_f32 v[4:5], v[4:5], v[242:243] op_sel_hi:[1,0]
	v_pk_mul_f32 v[10:11], v[10:11], v[244:245] op_sel_hi:[1,0]
	v_pk_mul_f32 v[8:9], v[8:9], v[244:245] op_sel_hi:[1,0]
	v_pk_mul_f32 v[14:15], v[14:15], v[246:247] op_sel_hi:[1,0]
	v_pk_mul_f32 v[12:13], v[12:13], v[246:247] op_sel_hi:[1,0]
	v_pk_mul_f32 v[18:19], v[18:19], v[248:249] op_sel_hi:[1,0]
	v_pk_mul_f32 v[16:17], v[16:17], v[248:249] op_sel_hi:[1,0]

.LBB0_294:
	v_add_u32_e32 v8, s42, v24
	v_ashrrev_i32_e32 v9, 31, v8
	v_mul_lo_u32 v5, s26, v9
	v_mul_lo_u32 v10, s27, v8
	v_mad_u64_u32 v[6:7], s[4:5], s26, v8, 0
	v_add3_u32 v7, v7, v5, v10
	v_lshl_add_u64 v[6:7], v[6:7], 2, s[28:29]
	v_ashrrev_i32_e32 v5, 31, v4
	v_lshl_add_u64 v[4:5], v[4:5], 2, v[6:7]
	v_lshl_add_u64 v[4:5], v[4:5], 0, v[2:3]
	global_load_dwordx4 v[4:7], v[4:5], off
	s_cmp_lg_u64 s[24:25], 0
	s_cselect_b64 s[30:31], -1, 0
	s_cmp_eq_u64 s[24:25], 0
	s_cbranch_scc1 .LBB0_296
	v_lshl_add_u64 v[8:9], v[8:9], 2, s[24:25]
	global_load_dword v242, v[8:9], off

.LBB0_298:
	v_add_u32_e32 v12, s42, v25
	v_ashrrev_i32_e32 v13, 31, v12
	v_mul_lo_u32 v9, s26, v13
	v_mul_lo_u32 v14, s27, v12
	v_mad_u64_u32 v[10:11], s[4:5], s26, v12, 0
	v_add3_u32 v11, v11, v9, v14
	v_lshl_add_u64 v[10:11], v[10:11], 2, s[28:29]
	v_ashrrev_i32_e32 v9, 31, v8
	v_lshl_add_u64 v[8:9], v[8:9], 2, v[10:11]
	v_lshl_add_u64 v[8:9], v[8:9], 0, v[2:3]
	global_load_dwordx4 v[8:11], v[8:9], off
	v_cndmask_b32_e64 v14, 0, 1, s[30:31]
	v_cmp_ne_u32_e64 s[4:5], 1, v14
	s_andn2_b64 vcc, exec, s[30:31]
	s_cbranch_vccnz .LBB0_300
	v_lshl_add_u64 v[12:13], v[12:13], 2, s[24:25]
	global_load_dword v244, v[12:13], off

.LBB0_302:
	v_add_u32_e32 v18, s42, v26
	v_ashrrev_i32_e32 v19, 31, v18
	v_mul_lo_u32 v13, s26, v19
	v_mul_lo_u32 v22, s27, v18
	v_mad_u64_u32 v[14:15], s[30:31], s26, v18, 0
	v_add3_u32 v15, v15, v13, v22
	v_lshl_add_u64 v[14:15], v[14:15], 2, s[28:29]
	v_ashrrev_i32_e32 v13, 31, v12
	v_lshl_add_u64 v[12:13], v[12:13], 2, v[14:15]
	v_lshl_add_u64 v[12:13], v[12:13], 0, v[2:3]
	global_load_dwordx4 v[12:15], v[12:13], off
	s_and_b64 vcc, exec, s[4:5]
	s_cbranch_vccnz .LBB0_304
	v_lshl_add_u64 v[18:19], v[18:19], 2, s[24:25]
	global_load_dword v246, v[18:19], off

.LBB0_306:
	v_add_u32_e32 v22, s42, v27
	v_ashrrev_i32_e32 v23, 31, v22
	v_mul_lo_u32 v17, s26, v23
	v_mul_lo_u32 v21, s27, v22
	v_mad_u64_u32 v[18:19], s[0:1], s26, v22, 0
	v_add3_u32 v19, v19, v17, v21
	v_lshl_add_u64 v[18:19], v[18:19], 2, s[28:29]
	v_ashrrev_i32_e32 v17, 31, v16
	v_lshl_add_u64 v[16:17], v[16:17], 2, v[18:19]
	v_lshl_add_u64 v[16:17], v[16:17], 0, v[2:3]
	global_load_dwordx4 v[16:19], v[16:17], off
	s_and_b64 vcc, exec, s[4:5]
	s_cbranch_vccnz .LBB0_283
	v_lshl_add_u64 v[22:23], v[22:23], 2, s[24:25]
	global_load_dword v248, v[22:23], off
	s_waitcnt vmcnt(0)
	v_pk_mul_f32 v[6:7], v[6:7], v[242:243] op_sel_hi:[1,0]
	v_pk_mul_f32 v[4:5], v[4:5], v[242:243] op_sel_hi:[1,0]
	v_pk_mul_f32 v[10:11], v[10:11], v[244:245] op_sel_hi:[1,0]
	v_pk_mul_f32 v[8:9], v[8:9], v[244:245] op_sel_hi:[1,0]
	v_pk_mul_f32 v[14:15], v[14:15], v[246:247] op_sel_hi:[1,0]
	v_pk_mul_f32 v[12:13], v[12:13], v[246:247] op_sel_hi:[1,0]
	v_pk_mul_f32 v[18:19], v[18:19], v[248:249] op_sel_hi:[1,0]
	v_pk_mul_f32 v[16:17], v[16:17], v[248:249] op_sel_hi:[1,0]
	s_branch .LBB0_283

.LBB0_423:
	v_ashrrev_i32_e32 v23, 5, v28
	v_add_u32_e32 v8, s8, v23
	v_ashrrev_i32_e32 v9, 31, v8
	v_mul_lo_u32 v5, s14, v9
	v_mul_lo_u32 v10, s15, v8
	v_mad_u64_u32 v[6:7], s[4:5], s14, v8, 0
	v_add3_u32 v7, v7, v5, v10
	v_and_b32_e32 v2, 60, v27
	v_lshl_add_u64 v[6:7], v[6:7], 2, s[12:13]
	v_ashrrev_i32_e32 v5, 31, v4
	v_lshl_add_u64 v[4:5], v[4:5], 2, v[6:7]
	v_lshlrev_b32_e32 v2, 2, v2
	v_lshl_add_u64 v[4:5], v[4:5], 0, v[2:3]
	global_load_dwordx4 v[4:7], v[4:5], off
	s_cmp_lg_u64 s[10:11], 0
	s_cselect_b64 s[16:17], -1, 0
	s_cmp_eq_u64 s[10:11], 0
	s_cbranch_scc1 .LBB0_425
	v_lshl_add_u64 v[8:9], v[8:9], 2, s[10:11]
	global_load_dword v242, v[8:9], off

.LBB0_427:
	v_add_u32_e32 v9, 0x200, v28
	v_ashrrev_i32_e32 v24, 5, v9
	v_add_u32_e32 v12, s8, v24
	v_ashrrev_i32_e32 v13, 31, v12
	v_mul_lo_u32 v9, s14, v13
	v_mul_lo_u32 v14, s15, v12
	v_mad_u64_u32 v[10:11], s[4:5], s14, v12, 0
	v_add3_u32 v11, v11, v9, v14
	v_lshl_add_u64 v[10:11], v[10:11], 2, s[12:13]
	v_ashrrev_i32_e32 v9, 31, v8
	v_lshl_add_u64 v[8:9], v[8:9], 2, v[10:11]
	v_lshl_add_u64 v[8:9], v[8:9], 0, v[2:3]
	global_load_dwordx4 v[8:11], v[8:9], off
	v_cndmask_b32_e64 v14, 0, 1, s[16:17]
	v_cmp_ne_u32_e64 s[4:5], 1, v14
	s_andn2_b64 vcc, exec, s[16:17]
	s_cbranch_vccnz .LBB0_429
	v_lshl_add_u64 v[12:13], v[12:13], 2, s[10:11]
	global_load_dword v244, v[12:13], off

.LBB0_431:
	v_add_u32_e32 v13, 0x400, v28
	v_ashrrev_i32_e32 v25, 5, v13
	v_add_u32_e32 v16, s8, v25
	v_ashrrev_i32_e32 v17, 31, v16
	v_mul_lo_u32 v13, s14, v17
	v_mul_lo_u32 v19, s15, v16
	v_mad_u64_u32 v[14:15], s[16:17], s14, v16, 0
	v_add3_u32 v15, v15, v13, v19
	v_lshl_add_u64 v[14:15], v[14:15], 2, s[12:13]
	v_ashrrev_i32_e32 v13, 31, v12
	v_lshl_add_u64 v[12:13], v[12:13], 2, v[14:15]
	v_lshl_add_u64 v[12:13], v[12:13], 0, v[2:3]
	global_load_dwordx4 v[12:15], v[12:13], off
	s_and_b64 vcc, exec, s[4:5]
	s_cbranch_vccnz .LBB0_433
	v_lshl_add_u64 v[16:17], v[16:17], 2, s[10:11]
	global_load_dword v246, v[16:17], off

.LBB0_435:
	v_add_u32_e32 v1, 0x600, v28
	v_ashrrev_i32_e32 v26, 5, v1
	v_add_u32_e32 v20, s8, v26
	v_ashrrev_i32_e32 v21, 31, v20
	v_mul_lo_u32 v1, s14, v21
	v_mul_lo_u32 v18, s15, v20
	v_mad_u64_u32 v[16:17], s[0:1], s14, v20, 0
	v_add3_u32 v17, v17, v1, v18
	v_lshl_add_u64 v[16:17], v[16:17], 2, s[12:13]
	v_ashrrev_i32_e32 v1, 31, v0
	v_lshl_add_u64 v[0:1], v[0:1], 2, v[16:17]
	v_lshl_add_u64 v[0:1], v[0:1], 0, v[2:3]
	global_load_dwordx4 v[16:19], v[0:1], off
	s_and_b64 vcc, exec, s[4:5]
	s_cbranch_vccnz .LBB0_437
	v_lshl_add_u64 v[0:1], v[20:21], 2, s[10:11]
	global_load_dword v248, v[0:1], off
	s_waitcnt vmcnt(0)
	v_pk_mul_f32 v[6:7], v[6:7], v[242:243] op_sel_hi:[1,0]
	v_pk_mul_f32 v[4:5], v[4:5], v[242:243] op_sel_hi:[1,0]
	v_pk_mul_f32 v[10:11], v[10:11], v[244:245] op_sel_hi:[1,0]
	v_pk_mul_f32 v[8:9], v[8:9], v[244:245] op_sel_hi:[1,0]
	v_pk_mul_f32 v[14:15], v[14:15], v[246:247] op_sel_hi:[1,0]
	v_pk_mul_f32 v[12:13], v[12:13], v[246:247] op_sel_hi:[1,0]
	v_pk_mul_f32 v[18:19], v[18:19], v[248:249] op_sel_hi:[1,0]
	v_pk_mul_f32 v[16:17], v[16:17], v[248:249] op_sel_hi:[1,0]

.LBB0_449:
	v_add_u32_e32 v8, s43, v23
	v_ashrrev_i32_e32 v9, 31, v8
	v_mul_lo_u32 v5, s28, v9
	v_mul_lo_u32 v10, s29, v8
	v_mad_u64_u32 v[6:7], s[4:5], s28, v8, 0
	v_add3_u32 v7, v7, v5, v10
	v_lshl_add_u64 v[6:7], v[6:7], 2, s[30:31]
	v_ashrrev_i32_e32 v5, 31, v4
	v_lshl_add_u64 v[4:5], v[4:5], 2, v[6:7]
	v_lshl_add_u64 v[4:5], v[4:5], 0, v[2:3]
	global_load_dwordx4 v[4:7], v[4:5], off
	s_cmp_lg_u64 s[26:27], 0
	s_cselect_b64 s[34:35], -1, 0
	s_cmp_eq_u64 s[26:27], 0
	s_cbranch_scc1 .LBB0_451
	v_lshl_add_u64 v[8:9], v[8:9], 2, s[26:27]
	global_load_dword v242, v[8:9], off

.LBB0_453:
	v_add_u32_e32 v12, s43, v24
	v_ashrrev_i32_e32 v13, 31, v12
	v_mul_lo_u32 v9, s28, v13
	v_mul_lo_u32 v14, s29, v12
	v_mad_u64_u32 v[10:11], s[4:5], s28, v12, 0
	v_add3_u32 v11, v11, v9, v14
	v_lshl_add_u64 v[10:11], v[10:11], 2, s[30:31]
	v_ashrrev_i32_e32 v9, 31, v8
	v_lshl_add_u64 v[8:9], v[8:9], 2, v[10:11]
	v_lshl_add_u64 v[8:9], v[8:9], 0, v[2:3]
	global_load_dwordx4 v[8:11], v[8:9], off
	v_cndmask_b32_e64 v14, 0, 1, s[34:35]
	v_cmp_ne_u32_e64 s[4:5], 1, v14
	s_andn2_b64 vcc, exec, s[34:35]
	s_cbranch_vccnz .LBB0_455
	v_lshl_add_u64 v[12:13], v[12:13], 2, s[26:27]
	global_load_dword v244, v[12:13], off

.LBB0_457:
	v_add_u32_e32 v18, s43, v25
	v_ashrrev_i32_e32 v19, 31, v18
	v_mul_lo_u32 v13, s28, v19
	v_mul_lo_u32 v20, s29, v18
	v_mad_u64_u32 v[14:15], s[34:35], s28, v18, 0
	v_add3_u32 v15, v15, v13, v20
	v_lshl_add_u64 v[14:15], v[14:15], 2, s[30:31]
	v_ashrrev_i32_e32 v13, 31, v12
	v_lshl_add_u64 v[12:13], v[12:13], 2, v[14:15]
	v_lshl_add_u64 v[12:13], v[12:13], 0, v[2:3]
	global_load_dwordx4 v[12:15], v[12:13], off
	s_and_b64 vcc, exec, s[4:5]
	s_cbranch_vccnz .LBB0_459
	v_lshl_add_u64 v[18:19], v[18:19], 2, s[26:27]
	global_load_dword v246, v[18:19], off

.LBB0_461:
	v_add_u32_e32 v20, s43, v26
	v_ashrrev_i32_e32 v21, 31, v20
	v_mul_lo_u32 v1, s28, v21
	v_mul_lo_u32 v17, s29, v20
	v_mad_u64_u32 v[18:19], s[0:1], s28, v20, 0
	v_add3_u32 v19, v19, v1, v17
	v_lshl_add_u64 v[18:19], v[18:19], 2, s[30:31]
	v_ashrrev_i32_e32 v17, 31, v16
	v_lshl_add_u64 v[16:17], v[16:17], 2, v[18:19]
	v_lshl_add_u64 v[16:17], v[16:17], 0, v[2:3]
	global_load_dwordx4 v[16:19], v[16:17], off
	s_and_b64 vcc, exec, s[4:5]
	s_cbranch_vccnz .LBB0_438
	v_lshl_add_u64 v[20:21], v[20:21], 2, s[26:27]
	global_load_dword v248, v[20:21], off
	s_waitcnt vmcnt(0)
	v_pk_mul_f32 v[6:7], v[6:7], v[242:243] op_sel_hi:[1,0]
	v_pk_mul_f32 v[4:5], v[4:5], v[242:243] op_sel_hi:[1,0]
	v_pk_mul_f32 v[10:11], v[10:11], v[244:245] op_sel_hi:[1,0]
	v_pk_mul_f32 v[8:9], v[8:9], v[244:245] op_sel_hi:[1,0]
	v_pk_mul_f32 v[14:15], v[14:15], v[246:247] op_sel_hi:[1,0]
	v_pk_mul_f32 v[12:13], v[12:13], v[246:247] op_sel_hi:[1,0]
	v_pk_mul_f32 v[18:19], v[18:19], v[248:249] op_sel_hi:[1,0]
	v_pk_mul_f32 v[16:17], v[16:17], v[248:249] op_sel_hi:[1,0]
	s_branch .LBB0_438

.LBB0_758:
	v_add_u32_e32 v8, s41, v23
	v_ashrrev_i32_e32 v9, 31, v8
	v_mul_lo_u32 v5, s26, v9
	v_mul_lo_u32 v10, s27, v8
	v_mad_u64_u32 v[6:7], s[4:5], s26, v8, 0
	v_add3_u32 v7, v7, v5, v10
	v_lshl_add_u64 v[6:7], v[6:7], 2, s[28:29]
	v_ashrrev_i32_e32 v5, 31, v4
	v_lshl_add_u64 v[4:5], v[4:5], 2, v[6:7]
	v_lshl_add_u64 v[4:5], v[4:5], 0, v[2:3]
	global_load_dwordx4 v[4:7], v[4:5], off
	s_cmp_lg_u64 s[24:25], 0
	s_cselect_b64 s[30:31], -1, 0
	s_cmp_eq_u64 s[24:25], 0
	s_cbranch_scc1 .LBB0_760
	v_lshl_add_u64 v[8:9], v[8:9], 2, s[24:25]
	global_load_dword v242, v[8:9], off

.LBB0_762:
	v_add_u32_e32 v12, s41, v24
	v_ashrrev_i32_e32 v13, 31, v12
	v_mul_lo_u32 v9, s26, v13
	v_mul_lo_u32 v14, s27, v12
	v_mad_u64_u32 v[10:11], s[4:5], s26, v12, 0
	v_add3_u32 v11, v11, v9, v14
	v_lshl_add_u64 v[10:11], v[10:11], 2, s[28:29]
	v_ashrrev_i32_e32 v9, 31, v8
	v_lshl_add_u64 v[8:9], v[8:9], 2, v[10:11]
	v_lshl_add_u64 v[8:9], v[8:9], 0, v[2:3]
	global_load_dwordx4 v[8:11], v[8:9], off
	v_cndmask_b32_e64 v14, 0, 1, s[30:31]
	v_cmp_ne_u32_e64 s[4:5], 1, v14
	s_andn2_b64 vcc, exec, s[30:31]
	s_cbranch_vccnz .LBB0_764
	v_lshl_add_u64 v[12:13], v[12:13], 2, s[24:25]
	global_load_dword v244, v[12:13], off

.LBB0_766:
	v_add_u32_e32 v18, s41, v25
	v_ashrrev_i32_e32 v19, 31, v18
	v_mul_lo_u32 v13, s26, v19
	v_mul_lo_u32 v20, s27, v18
	v_mad_u64_u32 v[14:15], s[30:31], s26, v18, 0
	v_add3_u32 v15, v15, v13, v20
	v_lshl_add_u64 v[14:15], v[14:15], 2, s[28:29]
	v_ashrrev_i32_e32 v13, 31, v12
	v_lshl_add_u64 v[12:13], v[12:13], 2, v[14:15]
	v_lshl_add_u64 v[12:13], v[12:13], 0, v[2:3]
	global_load_dwordx4 v[12:15], v[12:13], off
	s_and_b64 vcc, exec, s[4:5]
	s_cbranch_vccnz .LBB0_768
	v_lshl_add_u64 v[18:19], v[18:19], 2, s[24:25]
	global_load_dword v246, v[18:19], off

.LBB0_770:
	v_add_u32_e32 v20, s41, v26
	v_ashrrev_i32_e32 v21, 31, v20
	v_mul_lo_u32 v1, s26, v21
	v_mul_lo_u32 v17, s27, v20
	v_mad_u64_u32 v[18:19], s[0:1], s26, v20, 0
	v_add3_u32 v19, v19, v1, v17
	v_lshl_add_u64 v[18:19], v[18:19], 2, s[28:29]
	v_ashrrev_i32_e32 v17, 31, v16
	v_lshl_add_u64 v[16:17], v[16:17], 2, v[18:19]
	v_lshl_add_u64 v[16:17], v[16:17], 0, v[2:3]
	global_load_dwordx4 v[16:19], v[16:17], off
	s_and_b64 vcc, exec, s[4:5]
	s_cbranch_vccnz .LBB0_747
	v_lshl_add_u64 v[20:21], v[20:21], 2, s[24:25]
	global_load_dword v248, v[20:21], off
	s_waitcnt vmcnt(0)
	v_pk_mul_f32 v[6:7], v[6:7], v[242:243] op_sel_hi:[1,0]
	v_pk_mul_f32 v[4:5], v[4:5], v[242:243] op_sel_hi:[1,0]
	v_pk_mul_f32 v[10:11], v[10:11], v[244:245] op_sel_hi:[1,0]
	v_pk_mul_f32 v[8:9], v[8:9], v[244:245] op_sel_hi:[1,0]
	v_pk_mul_f32 v[14:15], v[14:15], v[246:247] op_sel_hi:[1,0]
	v_pk_mul_f32 v[12:13], v[12:13], v[246:247] op_sel_hi:[1,0]
	v_pk_mul_f32 v[18:19], v[18:19], v[248:249] op_sel_hi:[1,0]
	v_pk_mul_f32 v[16:17], v[16:17], v[248:249] op_sel_hi:[1,0]
	s_branch .LBB0_747

.LBB0_781:
	s_bfe_i32 s13, s7, 0x10007
	s_ashr_i32 s14, s7, 1
	s_and_b32 s13, s13, 0xb00
	s_and_b32 s14, s14, 0xffffff80
	s_add_i32 s13, s13, s14
	v_lshlrev_b32_e32 v27, 2, v28
	v_ashrrev_i32_e32 v23, 5, v28
	s_and_b64 s[0:1], s[0:1], exec
	v_and_b32_e32 v22, 64, v27
	s_cselect_b32 s0, s13, s7
	s_waitcnt vmcnt(2)
	v_add_u32_e32 v8, s6, v23
	v_or_b32_e32 v0, s0, v22
	v_mad_i64_i32 v[4:5], s[0:1], s12, v8, 0
	v_and_b32_e32 v2, 60, v27
	v_lshl_add_u64 v[4:5], v[4:5], 2, s[8:9]
	v_ashrrev_i32_e32 v1, 31, v0
	v_lshl_add_u64 v[4:5], v[0:1], 2, v[4:5]
	v_lshlrev_b32_e32 v2, 2, v2
	v_lshl_add_u64 v[4:5], v[4:5], 0, v[2:3]
	global_load_dwordx4 v[4:7], v[4:5], off
	s_cmp_lg_u64 s[10:11], 0
	s_cselect_b64 s[14:15], -1, 0
	s_cmp_eq_u64 s[10:11], 0
	s_cbranch_scc1 .LBB0_783
	v_ashrrev_i32_e32 v9, 31, v8
	v_lshl_add_u64 v[8:9], v[8:9], 2, s[10:11]
	global_load_dword v242, v[8:9], off
.LBB0_783:
	v_add_u32_e32 v8, 0x200, v28
	v_ashrrev_i32_e32 v24, 5, v8
	v_add_u32_e32 v12, s6, v24
	v_mad_i64_i32 v[8:9], s[0:1], s12, v12, 0
	v_lshl_add_u64 v[8:9], v[8:9], 2, s[8:9]
	v_lshl_add_u64 v[8:9], v[0:1], 2, v[8:9]
	v_lshl_add_u64 v[8:9], v[8:9], 0, v[2:3]
	global_load_dwordx4 v[8:11], v[8:9], off
	v_cndmask_b32_e64 v13, 0, 1, s[14:15]
	v_cmp_ne_u32_e64 s[0:1], 1, v13
	s_andn2_b64 vcc, exec, s[14:15]
	s_cbranch_vccnz .LBB0_785
	v_ashrrev_i32_e32 v13, 31, v12
	v_lshl_add_u64 v[12:13], v[12:13], 2, s[10:11]
	global_load_dword v244, v[12:13], off
.LBB0_785:
	v_add_u32_e32 v12, 0x400, v28
	v_ashrrev_i32_e32 v25, 5, v12
	v_add_u32_e32 v16, s6, v25
	v_mad_i64_i32 v[12:13], s[14:15], s12, v16, 0
	v_lshl_add_u64 v[12:13], v[12:13], 2, s[8:9]
	v_lshl_add_u64 v[12:13], v[0:1], 2, v[12:13]
	v_lshl_add_u64 v[12:13], v[12:13], 0, v[2:3]
	global_load_dwordx4 v[12:15], v[12:13], off
	s_and_b64 vcc, exec, s[0:1]
	s_cbranch_vccnz .LBB0_787
	v_ashrrev_i32_e32 v17, 31, v16
	v_lshl_add_u64 v[16:17], v[16:17], 2, s[10:11]
	global_load_dword v246, v[16:17], off
.LBB0_787:
	v_add_u32_e32 v16, 0x600, v28
	v_ashrrev_i32_e32 v26, 5, v16
	v_add_u32_e32 v20, s6, v26
	v_mad_i64_i32 v[16:17], s[12:13], s12, v20, 0
	v_lshl_add_u64 v[16:17], v[16:17], 2, s[8:9]
	v_lshl_add_u64 v[0:1], v[0:1], 2, v[16:17]
	v_lshl_add_u64 v[0:1], v[0:1], 0, v[2:3]
	global_load_dwordx4 v[16:19], v[0:1], off
	s_and_b64 vcc, exec, s[0:1]
	s_cbranch_vccnz .LBB0_789
	v_ashrrev_i32_e32 v21, 31, v20
	v_lshl_add_u64 v[0:1], v[20:21], 2, s[10:11]
	global_load_dword v248, v[0:1], off
	s_waitcnt vmcnt(0)
	v_pk_mul_f32 v[6:7], v[6:7], v[242:243] op_sel_hi:[1,0]
	v_pk_mul_f32 v[4:5], v[4:5], v[242:243] op_sel_hi:[1,0]
	v_pk_mul_f32 v[10:11], v[10:11], v[244:245] op_sel_hi:[1,0]
	v_pk_mul_f32 v[8:9], v[8:9], v[244:245] op_sel_hi:[1,0]
	v_pk_mul_f32 v[14:15], v[14:15], v[246:247] op_sel_hi:[1,0]
	v_pk_mul_f32 v[12:13], v[12:13], v[246:247] op_sel_hi:[1,0]
	v_pk_mul_f32 v[18:19], v[18:19], v[248:249] op_sel_hi:[1,0]
	v_pk_mul_f32 v[16:17], v[16:17], v[248:249] op_sel_hi:[1,0]

.LBB0_797:
	s_bfe_i32 s27, s38, 0x10007
	s_ashr_i32 s28, s38, 1
	s_and_b32 s27, s27, 0xb00
	s_and_b32 s28, s28, 0xffffff80
	s_add_i32 s27, s27, s28
	s_and_b64 s[0:1], s[0:1], exec
	s_cselect_b32 s0, s27, s38
	v_add_u32_e32 v8, s40, v23
	v_or_b32_e32 v16, s0, v22
	v_mad_i64_i32 v[4:5], s[0:1], s26, v8, 0
	v_lshl_add_u64 v[4:5], v[4:5], 2, s[24:25]
	v_ashrrev_i32_e32 v17, 31, v16
	v_lshl_add_u64 v[4:5], v[16:17], 2, v[4:5]
	v_lshl_add_u64 v[4:5], v[4:5], 0, v[2:3]
	global_load_dwordx4 v[4:7], v[4:5], off
	s_cmp_lg_u64 s[22:23], 0
	s_cselect_b64 s[28:29], -1, 0
	s_cmp_eq_u64 s[22:23], 0
	s_cbranch_scc1 .LBB0_799
	v_ashrrev_i32_e32 v9, 31, v8
	v_lshl_add_u64 v[8:9], v[8:9], 2, s[22:23]
	global_load_dword v242, v[8:9], off
.LBB0_799:
	v_add_u32_e32 v12, s40, v24
	v_mad_i64_i32 v[8:9], s[0:1], s26, v12, 0
	v_lshl_add_u64 v[8:9], v[8:9], 2, s[24:25]
	v_lshl_add_u64 v[8:9], v[16:17], 2, v[8:9]
	v_lshl_add_u64 v[8:9], v[8:9], 0, v[2:3]
	global_load_dwordx4 v[8:11], v[8:9], off
	v_cndmask_b32_e64 v1, 0, 1, s[28:29]
	v_cmp_ne_u32_e64 s[0:1], 1, v1
	s_andn2_b64 vcc, exec, s[28:29]
	s_cbranch_vccnz .LBB0_801
	v_ashrrev_i32_e32 v13, 31, v12
	v_lshl_add_u64 v[12:13], v[12:13], 2, s[22:23]
	global_load_dword v244, v[12:13], off
.LBB0_801:
	v_add_u32_e32 v18, s40, v25
	v_mad_i64_i32 v[12:13], s[28:29], s26, v18, 0
	v_lshl_add_u64 v[12:13], v[12:13], 2, s[24:25]
	v_lshl_add_u64 v[12:13], v[16:17], 2, v[12:13]
	v_lshl_add_u64 v[12:13], v[12:13], 0, v[2:3]
	global_load_dwordx4 v[12:15], v[12:13], off
	s_and_b64 vcc, exec, s[0:1]
	s_cbranch_vccnz .LBB0_803
	v_ashrrev_i32_e32 v19, 31, v18
	v_lshl_add_u64 v[18:19], v[18:19], 2, s[22:23]
	global_load_dword v246, v[18:19], off
.LBB0_803:
	v_add_u32_e32 v20, s40, v26
	v_mad_i64_i32 v[18:19], s[26:27], s26, v20, 0
	v_lshl_add_u64 v[18:19], v[18:19], 2, s[24:25]
	v_lshl_add_u64 v[16:17], v[16:17], 2, v[18:19]
	v_lshl_add_u64 v[16:17], v[16:17], 0, v[2:3]
	global_load_dwordx4 v[16:19], v[16:17], off
	s_and_b64 vcc, exec, s[0:1]
	s_cbranch_vccnz .LBB0_790
	v_ashrrev_i32_e32 v21, 31, v20
	v_lshl_add_u64 v[20:21], v[20:21], 2, s[22:23]
	global_load_dword v248, v[20:21], off
	s_waitcnt vmcnt(0)
	v_pk_mul_f32 v[6:7], v[6:7], v[242:243] op_sel_hi:[1,0]
	v_pk_mul_f32 v[4:5], v[4:5], v[242:243] op_sel_hi:[1,0]
	v_pk_mul_f32 v[10:11], v[10:11], v[244:245] op_sel_hi:[1,0]
	v_pk_mul_f32 v[8:9], v[8:9], v[244:245] op_sel_hi:[1,0]
	v_pk_mul_f32 v[14:15], v[14:15], v[246:247] op_sel_hi:[1,0]
	v_pk_mul_f32 v[12:13], v[12:13], v[246:247] op_sel_hi:[1,0]
	v_pk_mul_f32 v[18:19], v[18:19], v[248:249] op_sel_hi:[1,0]
	v_pk_mul_f32 v[16:17], v[16:17], v[248:249] op_sel_hi:[1,0]
	s_branch .LBB0_790
